# stack: unit-boundary priority raise + waves 4-7 leading the GEMM ping-pong
# baseline (speedup 1.0000x reference)
.LBB0_48:
	s_waitcnt vmcnt(0)
	s_setprio 0
	s_cmpk_lt_u32 s9, 0x100
	s_cbranch_scc1 .LBB0_50
	s_barrier
